# chain step: gate LDS reads software-pipelined (double-buffered into kT regs, round 0 hoisted under last O MFMA group, kT reads deferred)
# baseline (speedup 1.0000x reference)
.LBB0_203:
	s_or_b64 exec, exec, s[2:3]
	v_add_u32_e32 v190, 0x2000, v224
	ds_read2_b64 v[66:69], v224 offset1:2
	ds_read2_b64 v[170:173], v224 offset0:4 offset1:6
	ds_read2_b64 v[70:73], v190 offset0:64 offset1:66
	ds_read2_b64 v[174:177], v190 offset0:68 offset1:70
	ds_read2_b64 v[178:181], v224 offset0:8 offset1:10
	ds_read2_b64 v[182:185], v190 offset0:72 offset1:74
	ds_read2_b64 v[234:237], v224 offset0:12 offset1:14
	ds_read2_b64 v[238:241], v190 offset0:76 offset1:78
	s_add_i32 s7, s8, -3
	s_and_b64 s[2:3], s[4:5], exec
	s_cselect_b32 s2, s7, s6
	s_add_i32 s2, s2, s37
	v_cvt_pk_bf16_f32 v74, v50, v51
	v_cvt_pk_bf16_f32 v75, v52, v53
	v_cvt_pk_bf16_f32 v76, v54, v55
	v_cvt_pk_bf16_f32 v77, v56, v57
	v_cvt_pk_bf16_f32 v242, v58, v59
	v_cvt_pk_bf16_f32 v243, v60, v61
	s_waitcnt lgkmcnt(7)
	v_mfma_f32_32x32x16_bf16 v[82:97], v[74:77], v[66:69], 0
	v_cvt_pk_bf16_f32 v244, v62, v63
	v_cvt_pk_bf16_f32 v245, v64, v65
	s_waitcnt lgkmcnt(5)
	v_mfma_f32_32x32x16_bf16 v[66:81], v[74:77], v[70:73], 0
	v_mfma_f32_32x32x16_bf16 v[82:97], v[242:245], v[170:173], v[82:97]
	s_waitcnt lgkmcnt(4)
	v_mfma_f32_32x32x16_bf16 v[66:81], v[242:245], v[174:177], v[66:81]
	ds_read2_b64 v[170:173], v224 offset0:16 offset1:18
	ds_read2_b64 v[174:177], v224 offset0:20 offset1:22
	ds_read2_b64 v[242:245], v190 offset0:80 offset1:82
	ds_read2_b64 v[246:249], v190 offset0:84 offset1:86
	v_cvt_pk_bf16_f32 v194, v34, v35
	v_cvt_pk_bf16_f32 v195, v36, v37
	v_cvt_pk_bf16_f32 v196, v38, v39
	v_cvt_pk_bf16_f32 v197, v40, v41
	s_waitcnt lgkmcnt(7)
	s_nop 0
	v_mfma_f32_32x32x16_bf16 v[82:97], v[194:197], v[178:181], v[82:97]
	v_cvt_pk_bf16_f32 v178, v42, v43
	v_cvt_pk_bf16_f32 v179, v44, v45
	v_cvt_pk_bf16_f32 v180, v46, v47
	v_cvt_pk_bf16_f32 v181, v48, v49
	s_waitcnt lgkmcnt(6)
	v_mfma_f32_32x32x16_bf16 v[66:81], v[194:197], v[182:185], v[66:81]
	s_waitcnt lgkmcnt(5)
	v_mfma_f32_32x32x16_bf16 v[82:97], v[178:181], v[234:237], v[82:97]
	s_waitcnt lgkmcnt(4)
	v_mfma_f32_32x32x16_bf16 v[66:81], v[178:181], v[238:241], v[66:81]
	ds_read2_b64 v[194:197], v224 offset0:24 offset1:26
	ds_read2_b64 v[234:237], v224 offset0:28 offset1:30
	ds_read2_b64 v[238:241], v190 offset0:88 offset1:90
	ds_read2_b64 v[190:193], v190 offset0:92 offset1:94
	v_cvt_pk_bf16_f32 v178, v18, v19
	v_cvt_pk_bf16_f32 v179, v20, v21
	v_cvt_pk_bf16_f32 v180, v22, v23
	v_cvt_pk_bf16_f32 v181, v24, v25
	s_waitcnt lgkmcnt(7)
	s_nop 0
	v_mfma_f32_32x32x16_bf16 v[82:97], v[178:181], v[170:173], v[82:97]
	v_cvt_pk_bf16_f32 v170, v26, v27
	v_cvt_pk_bf16_f32 v171, v28, v29
	v_cvt_pk_bf16_f32 v172, v30, v31
	v_cvt_pk_bf16_f32 v173, v32, v33
	s_waitcnt lgkmcnt(5)
	v_mfma_f32_32x32x16_bf16 v[66:81], v[178:181], v[242:245], v[66:81]
	v_mfma_f32_32x32x16_bf16 v[82:97], v[170:173], v[174:177], v[82:97]
	s_waitcnt lgkmcnt(4)
	v_mfma_f32_32x32x16_bf16 v[66:81], v[170:173], v[246:249], v[66:81]
	ds_read_b128 v[182:185], v221 offset:35840
	ds_read_b128 v[178:181], v221 offset:35872
	ds_read_b128 v[174:177], v221 offset:35904
	ds_read_b128 v[170:173], v221 offset:35936
	v_cvt_pk_bf16_f32 v242, v2, v3
	v_cvt_pk_bf16_f32 v243, v4, v5
	v_cvt_pk_bf16_f32 v244, v6, v7
	v_cvt_pk_bf16_f32 v245, v8, v9
	s_waitcnt lgkmcnt(7)
	s_nop 0
	v_mfma_f32_32x32x16_bf16 v[82:97], v[242:245], v[194:197], v[82:97]
	v_cvt_pk_bf16_f32 v194, v10, v11
	v_cvt_pk_bf16_f32 v195, v12, v13
	v_cvt_pk_bf16_f32 v196, v14, v15
	v_cvt_pk_bf16_f32 v197, v16, v17
	s_waitcnt lgkmcnt(5)
	v_mfma_f32_32x32x16_bf16 v[66:81], v[242:245], v[238:241], v[66:81]
	v_mfma_f32_32x32x16_bf16 v[82:97], v[194:197], v[234:237], v[82:97]
	s_waitcnt lgkmcnt(4)
	v_mfma_f32_32x32x16_bf16 v[66:81], v[194:197], v[190:193], v[66:81]
	ds_read_b128 v[190:193], v221 offset:35968
	ds_read_b128 v[194:197], v221 offset:36000
	ds_read_b128 v[234:237], v221 offset:36032
	ds_read_b128 v[238:241], v221 offset:36064
	s_waitcnt lgkmcnt(7)
	v_mul_f32_e32 v52, v52, v184
	v_mul_f32_e32 v53, v53, v185
	s_waitcnt lgkmcnt(6)
	v_mul_f32_e32 v56, v56, v180
	v_mul_f32_e32 v57, v57, v181
	s_waitcnt lgkmcnt(5)
	v_mul_f32_e32 v60, v60, v176
	v_mul_f32_e32 v61, v61, v177
	s_waitcnt lgkmcnt(4)
	v_mul_f32_e32 v64, v64, v172
	v_mul_f32_e32 v65, v65, v173
	v_mul_f32_e32 v62, v62, v170
	v_mul_f32_e32 v63, v63, v171
	v_mul_f32_e32 v58, v58, v174
	v_mul_f32_e32 v59, v59, v175
	v_mul_f32_e32 v54, v54, v178
	v_mul_f32_e32 v55, v55, v179
	v_mul_f32_e32 v50, v50, v182
	v_mul_f32_e32 v51, v51, v183
	ds_read_b128 v[182:185], v221 offset:36096
	ds_read_b128 v[178:181], v221 offset:36128
	ds_read_b128 v[174:177], v221 offset:36160
	ds_read_b128 v[170:173], v221 offset:36192
	s_waitcnt lgkmcnt(7)
	v_mul_f32_e32 v36, v36, v192
	v_mul_f32_e32 v37, v37, v193
	s_waitcnt lgkmcnt(6)
	v_mul_f32_e32 v40, v40, v196
	v_mul_f32_e32 v41, v41, v197
	s_waitcnt lgkmcnt(5)
	v_mul_f32_e32 v44, v44, v236
	v_mul_f32_e32 v45, v45, v237
	s_waitcnt lgkmcnt(4)
	v_mul_f32_e32 v48, v48, v240
	v_mul_f32_e32 v49, v49, v241
	v_mul_f32_e32 v46, v46, v238
	v_mul_f32_e32 v47, v47, v239
	v_mul_f32_e32 v42, v42, v234
	v_mul_f32_e32 v43, v43, v235
	v_mul_f32_e32 v38, v38, v194
	v_mul_f32_e32 v39, v39, v195
	v_mul_f32_e32 v34, v34, v190
	v_mul_f32_e32 v35, v35, v191
	ds_read_b128 v[190:193], v221 offset:36224
	ds_read_b128 v[194:197], v221 offset:36256
	ds_read_b128 v[234:237], v221 offset:36288
	ds_read_b128 v[238:241], v221 offset:36320
	s_waitcnt lgkmcnt(7)
	v_mul_f32_e32 v20, v20, v184
	v_mul_f32_e32 v21, v21, v185
	s_waitcnt lgkmcnt(6)
	v_mul_f32_e32 v24, v24, v180
	v_mul_f32_e32 v25, v25, v181
	s_waitcnt lgkmcnt(5)
	v_mul_f32_e32 v28, v28, v176
	v_mul_f32_e32 v29, v29, v177
	s_waitcnt lgkmcnt(4)
	v_mul_f32_e32 v32, v32, v172
	v_mul_f32_e32 v33, v33, v173
	v_mul_f32_e32 v30, v30, v170
	v_mul_f32_e32 v31, v31, v171
	v_mul_f32_e32 v26, v26, v174
	v_mul_f32_e32 v27, v27, v175
	v_mul_f32_e32 v22, v22, v178
	v_mul_f32_e32 v23, v23, v179
	v_mul_f32_e32 v18, v18, v182
	v_mul_f32_e32 v19, v19, v183
	ds_read_b128 v[182:185], v226 offset:17408
	ds_read_b128 v[178:181], v226 offset:17440
	ds_read_b128 v[174:177], v226 offset:17472
	ds_read_b128 v[170:173], v226 offset:17504
	s_waitcnt lgkmcnt(7)
	v_mul_f32_e32 v4, v4, v192
	v_mul_f32_e32 v5, v5, v193
	s_waitcnt lgkmcnt(6)
	v_mul_f32_e32 v8, v8, v196
	v_mul_f32_e32 v9, v9, v197
	s_waitcnt lgkmcnt(5)
	v_mul_f32_e32 v12, v12, v236
	v_mul_f32_e32 v13, v13, v237
	s_waitcnt lgkmcnt(4)
	v_mul_f32_e32 v16, v16, v240
	v_mul_f32_e32 v17, v17, v241
	v_mul_f32_e32 v14, v14, v238
	v_mul_f32_e32 v15, v15, v239
	v_mul_f32_e32 v10, v10, v234
	v_mul_f32_e32 v11, v11, v235
	v_mul_f32_e32 v6, v6, v194
	v_mul_f32_e32 v7, v7, v195
	v_mul_f32_e32 v2, v2, v190
	v_mul_f32_e32 v3, v3, v191
	ds_read_b128 v[190:193], v227 offset:17408
	ds_read_b128 v[194:197], v227 offset:17440
	ds_read_b128 v[234:237], v227 offset:17472
	ds_read_b128 v[238:241], v227 offset:17504
	s_waitcnt vmcnt(15) lgkmcnt(7)
	v_mfma_f32_32x32x16_bf16 v[50:65], v[182:185], v[114:117], v[50:65]
	s_waitcnt vmcnt(14) lgkmcnt(6)
	v_mfma_f32_32x32x16_bf16 v[50:65], v[178:181], v[110:113], v[50:65]
	s_waitcnt vmcnt(13) lgkmcnt(5)
	v_mfma_f32_32x32x16_bf16 v[50:65], v[174:177], v[106:109], v[50:65]
	s_waitcnt vmcnt(12) lgkmcnt(4)
	v_mfma_f32_32x32x16_bf16 v[50:65], v[170:173], v[102:105], v[50:65]
	v_lshl_or_b32 v242, s2, 6, v219
	v_ashrrev_i32_e32 v243, 31, v242
	v_lshlrev_b64 v[244:245], 11, v[242:243]
	v_lshl_add_u64 v[244:245], v[202:203], 0, v[244:245]
	v_cvt_pk_bf16_f32 v82, v82, v83
	v_cvt_pk_bf16_f32 v83, v84, v85
	v_cvt_pk_bf16_f32 v84, v90, v91
	v_cvt_pk_bf16_f32 v85, v92, v93
	v_cvt_pk_bf16_f32 v86, v86, v87
	v_cvt_pk_bf16_f32 v87, v88, v89
	v_cvt_pk_bf16_f32 v88, v94, v95
	v_cvt_pk_bf16_f32 v89, v96, v97
	v_or_b32_e32 v90, 32, v242
	v_ashrrev_i32_e32 v91, 31, v90
	v_permlane32_swap_b32_e32 v82, v84
	v_permlane32_swap_b32_e32 v83, v85
	v_permlane32_swap_b32_e32 v86, v88
	v_permlane32_swap_b32_e32 v87, v89
	global_store_dwordx4 v[244:245], v[82:85], off
	global_store_dwordx4 v[244:245], v[86:89], off offset:16
	v_lshlrev_b64 v[90:91], 11, v[90:91]
	v_lshl_add_u64 v[90:91], v[202:203], 0, v[90:91]
	v_cvt_pk_bf16_f32 v66, v66, v67
	v_cvt_pk_bf16_f32 v67, v68, v69
	v_cvt_pk_bf16_f32 v68, v74, v75
	v_cvt_pk_bf16_f32 v69, v76, v77
	v_cvt_pk_bf16_f32 v70, v70, v71
	v_cvt_pk_bf16_f32 v71, v72, v73
	v_cvt_pk_bf16_f32 v72, v78, v79
	v_cvt_pk_bf16_f32 v73, v80, v81
	s_nop 1
	v_permlane32_swap_b32_e32 v66, v68
	v_permlane32_swap_b32_e32 v67, v69
	v_permlane32_swap_b32_e32 v70, v72
	v_permlane32_swap_b32_e32 v71, v73
	global_store_dwordx4 v[90:91], v[66:69], off
	global_store_dwordx4 v[90:91], v[70:73], off offset:16
	s_waitcnt vmcnt(15)
	ds_write_b128 v187, v[118:121] offset:36864
	s_waitcnt vmcnt(14)
	ds_write_b128 v187, v[122:125] offset:45568
	s_waitcnt vmcnt(13)
	ds_write_b128 v220, v[130:133] offset:54272
	s_waitcnt vmcnt(12)
	ds_write_b128 v220, v[134:137] offset:63488
	s_and_saveexec_b64 s[14:15], vcc
	v_add_u32_e32 v66, 0x11c00, v228
	ds_write_b128 v66, v[126:129]
	s_or_b64 exec, exec, s[14:15]
	ds_read_b128 v[170:173], v225 offset:26624
	ds_read_b128 v[174:177], v225 offset:26656
	ds_read_b128 v[178:181], v225 offset:26688
	ds_read_b128 v[182:185], v225 offset:26720
	s_waitcnt lgkmcnt(7)
	v_mfma_f32_32x32x16_bf16 v[34:49], v[190:193], v[114:117], v[34:49]
	s_waitcnt lgkmcnt(6)
	v_mfma_f32_32x32x16_bf16 v[34:49], v[194:197], v[110:113], v[34:49]
	s_waitcnt lgkmcnt(5)
	v_mfma_f32_32x32x16_bf16 v[34:49], v[234:237], v[106:109], v[34:49]
	s_waitcnt lgkmcnt(4)
	v_mfma_f32_32x32x16_bf16 v[34:49], v[238:241], v[102:105], v[34:49]
	ds_read_b128 v[190:193], v225 offset:31232
	ds_read_b128 v[194:197], v225 offset:31264
	ds_read_b128 v[234:237], v225 offset:31296
	ds_read_b128 v[238:241], v225 offset:31328
	s_waitcnt lgkmcnt(7)
	v_mfma_f32_32x32x16_bf16 v[18:33], v[170:173], v[114:117], v[18:33]
	s_waitcnt lgkmcnt(6)
	v_mfma_f32_32x32x16_bf16 v[18:33], v[174:177], v[110:113], v[18:33]
	s_waitcnt lgkmcnt(5)
	v_mfma_f32_32x32x16_bf16 v[18:33], v[178:181], v[106:109], v[18:33]
	s_waitcnt lgkmcnt(4)
	v_mfma_f32_32x32x16_bf16 v[18:33], v[182:185], v[102:105], v[18:33]
	s_waitcnt lgkmcnt(3)
	v_mfma_f32_32x32x16_bf16 v[2:17], v[190:193], v[114:117], v[2:17]
	s_waitcnt lgkmcnt(2)
	v_mfma_f32_32x32x16_bf16 v[2:17], v[194:197], v[110:113], v[2:17]
	s_waitcnt lgkmcnt(1)
	v_mfma_f32_32x32x16_bf16 v[2:17], v[234:237], v[106:109], v[2:17]
	s_waitcnt lgkmcnt(0)
	v_mfma_f32_32x32x16_bf16 v[2:17], v[238:241], v[102:105], v[2:17]
	s_lshl_b64 s[0:1], s[0:1], 15
	v_lshl_add_u64 v[102:103], v[206:207], 0, s[0:1]
	global_load_dwordx4 v[114:117], v[102:103], off
	global_load_dwordx4 v[110:113], v[102:103], off offset:32
	global_load_dwordx4 v[106:109], v[102:103], off offset:64
	s_nop 0
	global_load_dwordx4 v[102:105], v[102:103], off offset:96
	v_mov_b32_e32 v66, s8
	s_min_u32 s2, s8, s52
	v_sub_u32_e64 v66, s52, v66 clamp
	s_and_b64 s[0:1], s[4:5], exec
	v_readfirstlane_b32 s0, v66
	s_cselect_b32 s0, s2, s0
	s_add_i32 s2, s0, s37
	v_lshl_add_u32 v68, s2, 6, v218
	v_mad_i64_i32 v[66:67], s[0:1], v68, s28, v[200:201]
	v_add_u32_e32 v68, 32, v68
	v_mad_i64_i32 v[68:69], s[0:1], v68, s28, v[200:201]
	s_lshl_b32 s0, s2, 2
	s_or_b32 s0, s0, s12
	s_ashr_i32 s1, s0, 31
	s_lshl_b64 s[2:3], s[0:1], 14
	s_add_u32 s2, s36, s2
	s_addc_u32 s3, s13, s3
	s_waitcnt lgkmcnt(0)
	s_barrier
	global_load_dwordx4 v[118:121], v[66:67], off
	global_load_dwordx4 v[122:125], v[68:69], off
	v_lshl_add_u64 v[66:67], v[188:189], 1, s[2:3]
	v_lshl_add_u64 v[66:67], v[66:67], 0, v[0:1]
	v_lshl_add_u64 v[68:69], v[198:199], 1, s[2:3]
	v_lshl_add_u64 v[68:69], v[68:69], 0, v[0:1]
	global_load_dwordx4 v[130:133], v[66:67], off
	global_load_dwordx4 v[134:137], v[68:69], off
	s_and_saveexec_b64 s[2:3], vcc
	s_cbranch_execz .LBB0_207
	s_lshl_b64 s[14:15], s[0:1], 9
	v_lshl_add_u64 v[66:67], v[204:205], 0, s[14:15]
	global_load_dwordx4 v[126:129], v[66:67], off
.LBB0_207:
	s_or_b64 exec, exec, s[2:3]
	v_add_u32_e32 v229, 0x9000, v224
	v_add_u32_e32 v246, 0xb000, v224
	ds_read2_b64 v[66:69], v229 offset1:2
	ds_read2_b64 v[170:173], v229 offset0:4 offset1:6
	ds_read2_b64 v[70:73], v246 offset0:64 offset1:66
	ds_read2_b64 v[174:177], v246 offset0:68 offset1:70
	ds_read2_b64 v[178:181], v229 offset0:8 offset1:10
	ds_read2_b64 v[182:185], v246 offset0:72 offset1:74
	ds_read2_b64 v[190:193], v229 offset0:12 offset1:14
	ds_read2_b64 v[194:197], v246 offset0:76 offset1:78
	s_xor_b32 s2, s7, 0x3fffffe
	s_add_i32 s3, s2, s81
	s_add_i32 s2, s7, 1
	s_and_b64 s[14:15], s[4:5], exec
	s_cselect_b32 s3, s2, s3
	s_add_i32 s3, s3, s37
	v_cvt_pk_bf16_f32 v74, v50, v51
	v_cvt_pk_bf16_f32 v75, v52, v53
	v_cvt_pk_bf16_f32 v76, v54, v55
	v_cvt_pk_bf16_f32 v77, v56, v57
	v_cvt_pk_bf16_f32 v234, v58, v59
	v_cvt_pk_bf16_f32 v235, v60, v61
	s_waitcnt lgkmcnt(7)
	v_mfma_f32_32x32x16_bf16 v[82:97], v[74:77], v[66:69], 0
	v_cvt_pk_bf16_f32 v236, v62, v63
	v_cvt_pk_bf16_f32 v237, v64, v65
	s_waitcnt lgkmcnt(5)
	v_mfma_f32_32x32x16_bf16 v[66:81], v[74:77], v[70:73], 0
	v_mfma_f32_32x32x16_bf16 v[82:97], v[234:237], v[170:173], v[82:97]
	s_waitcnt lgkmcnt(4)
	v_mfma_f32_32x32x16_bf16 v[66:81], v[234:237], v[174:177], v[66:81]
	ds_read2_b64 v[170:173], v229 offset0:16 offset1:18
	ds_read2_b64 v[174:177], v229 offset0:20 offset1:22
	ds_read2_b64 v[234:237], v246 offset0:80 offset1:82
	ds_read2_b64 v[238:241], v246 offset0:84 offset1:86
	v_cvt_pk_bf16_f32 v242, v34, v35
	v_cvt_pk_bf16_f32 v243, v36, v37
	v_cvt_pk_bf16_f32 v244, v38, v39
	v_cvt_pk_bf16_f32 v245, v40, v41
	s_waitcnt lgkmcnt(7)
	s_nop 0
	v_mfma_f32_32x32x16_bf16 v[82:97], v[242:245], v[178:181], v[82:97]
	v_cvt_pk_bf16_f32 v178, v42, v43
	v_cvt_pk_bf16_f32 v179, v44, v45
	v_cvt_pk_bf16_f32 v180, v46, v47
	v_cvt_pk_bf16_f32 v181, v48, v49
	s_waitcnt lgkmcnt(6)
	v_mfma_f32_32x32x16_bf16 v[66:81], v[242:245], v[182:185], v[66:81]
	s_waitcnt lgkmcnt(5)
	v_mfma_f32_32x32x16_bf16 v[82:97], v[178:181], v[190:193], v[82:97]
	s_waitcnt lgkmcnt(4)
	v_mfma_f32_32x32x16_bf16 v[66:81], v[178:181], v[194:197], v[66:81]
	ds_read2_b64 v[190:193], v229 offset0:24 offset1:26
	ds_read2_b64 v[194:197], v229 offset0:28 offset1:30
	ds_read2_b64 v[242:245], v246 offset0:88 offset1:90
	ds_read2_b64 v[246:249], v246 offset0:92 offset1:94
	v_cvt_pk_bf16_f32 v178, v18, v19
	v_cvt_pk_bf16_f32 v179, v20, v21
	v_cvt_pk_bf16_f32 v180, v22, v23
	v_cvt_pk_bf16_f32 v181, v24, v25
	s_waitcnt lgkmcnt(7)
	s_nop 0
	v_mfma_f32_32x32x16_bf16 v[82:97], v[178:181], v[170:173], v[82:97]
	v_cvt_pk_bf16_f32 v170, v26, v27
	v_cvt_pk_bf16_f32 v171, v28, v29
	v_cvt_pk_bf16_f32 v172, v30, v31
	v_cvt_pk_bf16_f32 v173, v32, v33
	s_waitcnt lgkmcnt(5)
	v_mfma_f32_32x32x16_bf16 v[66:81], v[178:181], v[234:237], v[66:81]
	v_mfma_f32_32x32x16_bf16 v[82:97], v[170:173], v[174:177], v[82:97]
	s_waitcnt lgkmcnt(4)
	v_mfma_f32_32x32x16_bf16 v[66:81], v[170:173], v[238:241], v[66:81]
	v_add_u32_e32 v229, 0x11c00, v186
	ds_read_b128 v[182:185], v229
	ds_read_b128 v[178:181], v229 offset:32
	ds_read_b128 v[174:177], v229 offset:64
	ds_read_b128 v[170:173], v229 offset:96
	v_cvt_pk_bf16_f32 v234, v2, v3
	v_cvt_pk_bf16_f32 v235, v4, v5
	v_cvt_pk_bf16_f32 v236, v6, v7
	v_cvt_pk_bf16_f32 v237, v8, v9
	s_waitcnt lgkmcnt(7)
	s_nop 0
	v_mfma_f32_32x32x16_bf16 v[82:97], v[234:237], v[190:193], v[82:97]
	v_cvt_pk_bf16_f32 v190, v10, v11
	v_cvt_pk_bf16_f32 v191, v12, v13
	v_cvt_pk_bf16_f32 v192, v14, v15
	v_cvt_pk_bf16_f32 v193, v16, v17
	s_waitcnt lgkmcnt(5)
	v_mfma_f32_32x32x16_bf16 v[66:81], v[234:237], v[242:245], v[66:81]
	v_mfma_f32_32x32x16_bf16 v[82:97], v[190:193], v[194:197], v[82:97]
	s_waitcnt lgkmcnt(4)
	v_mfma_f32_32x32x16_bf16 v[66:81], v[190:193], v[246:249], v[66:81]
	ds_read_b128 v[190:193], v229 offset:128
	ds_read_b128 v[194:197], v229 offset:160
	ds_read_b128 v[234:237], v229 offset:192
	ds_read_b128 v[238:241], v229 offset:224
	s_waitcnt lgkmcnt(7)
	v_mul_f32_e32 v52, v52, v184
	v_mul_f32_e32 v53, v53, v185
	s_waitcnt lgkmcnt(6)
	v_mul_f32_e32 v54, v54, v178
	v_mul_f32_e32 v55, v55, v179
	s_waitcnt lgkmcnt(5)
	v_mul_f32_e32 v58, v58, v174
	v_mul_f32_e32 v59, v59, v175
	s_waitcnt lgkmcnt(4)
	v_mul_f32_e32 v62, v62, v170
	v_mul_f32_e32 v63, v63, v171
	v_mul_f32_e32 v64, v64, v172
	v_mul_f32_e32 v65, v65, v173
	v_mul_f32_e32 v60, v60, v176
	v_mul_f32_e32 v61, v61, v177
	v_mul_f32_e32 v56, v56, v180
	v_mul_f32_e32 v57, v57, v181
	v_mul_f32_e32 v50, v50, v182
	v_mul_f32_e32 v51, v51, v183
	ds_read_b128 v[182:185], v229 offset:256
	ds_read_b128 v[178:181], v229 offset:288
	ds_read_b128 v[174:177], v229 offset:320
	ds_read_b128 v[170:173], v229 offset:352
	s_waitcnt lgkmcnt(7)
	v_mul_f32_e32 v36, v36, v192
	v_mul_f32_e32 v37, v37, v193
	s_waitcnt lgkmcnt(6)
	v_mul_f32_e32 v38, v38, v194
	v_mul_f32_e32 v39, v39, v195
	s_waitcnt lgkmcnt(5)
	v_mul_f32_e32 v42, v42, v234
	v_mul_f32_e32 v43, v43, v235
	s_waitcnt lgkmcnt(4)
	v_mul_f32_e32 v46, v46, v238
	v_mul_f32_e32 v47, v47, v239
	v_mul_f32_e32 v48, v48, v240
	v_mul_f32_e32 v49, v49, v241
	v_mul_f32_e32 v44, v44, v236
	v_mul_f32_e32 v45, v45, v237
	v_mul_f32_e32 v40, v40, v196
	v_mul_f32_e32 v41, v41, v197
	v_mul_f32_e32 v34, v34, v190
	v_mul_f32_e32 v35, v35, v191
	ds_read_b128 v[190:193], v229 offset:384
	ds_read_b128 v[194:197], v229 offset:416
	ds_read_b128 v[234:237], v229 offset:448
	ds_read_b128 v[238:241], v229 offset:480
	s_waitcnt lgkmcnt(7)
	v_mul_f32_e32 v20, v20, v184
	v_mul_f32_e32 v21, v21, v185
	s_waitcnt lgkmcnt(6)
	v_mul_f32_e32 v22, v22, v178
	v_mul_f32_e32 v23, v23, v179
	s_waitcnt lgkmcnt(5)
	v_mul_f32_e32 v26, v26, v174
	v_mul_f32_e32 v27, v27, v175
	s_waitcnt lgkmcnt(4)
	v_mul_f32_e32 v30, v30, v170
	v_mul_f32_e32 v31, v31, v171
	v_mul_f32_e32 v32, v32, v172
	v_mul_f32_e32 v33, v33, v173
	v_mul_f32_e32 v28, v28, v176
	v_mul_f32_e32 v29, v29, v177
	v_mul_f32_e32 v24, v24, v180
	v_mul_f32_e32 v25, v25, v181
	v_mul_f32_e32 v18, v18, v182
	v_mul_f32_e32 v19, v19, v183
	ds_read_b128 v[182:185], v226 offset:54272
	ds_read_b128 v[178:181], v226 offset:54304
	ds_read_b128 v[174:177], v226 offset:54336
	ds_read_b128 v[170:173], v226 offset:54368
	s_waitcnt lgkmcnt(7)
	v_mul_f32_e32 v4, v4, v192
	v_mul_f32_e32 v5, v5, v193
	s_waitcnt lgkmcnt(6)
	v_mul_f32_e32 v6, v6, v194
	v_mul_f32_e32 v7, v7, v195
	s_waitcnt lgkmcnt(5)
	v_mul_f32_e32 v10, v10, v234
	v_mul_f32_e32 v11, v11, v235
	s_waitcnt lgkmcnt(4)
	v_mul_f32_e32 v14, v14, v238
	v_mul_f32_e32 v15, v15, v239
	v_mul_f32_e32 v16, v16, v240
	v_mul_f32_e32 v17, v17, v241
	v_mul_f32_e32 v12, v12, v236
	v_mul_f32_e32 v13, v13, v237
	v_mul_f32_e32 v8, v8, v196
	v_mul_f32_e32 v9, v9, v197
	v_mul_f32_e32 v2, v2, v190
	v_mul_f32_e32 v3, v3, v191
	ds_read_b128 v[190:193], v227 offset:54272
	ds_read_b128 v[194:197], v227 offset:54304
	ds_read_b128 v[234:237], v227 offset:54336
	ds_read_b128 v[238:241], v227 offset:54368
	s_waitcnt vmcnt(19) lgkmcnt(7)
	v_mfma_f32_32x32x16_bf16 v[50:65], v[182:185], v[150:153], v[50:65]
	s_waitcnt vmcnt(18) lgkmcnt(6)
	v_mfma_f32_32x32x16_bf16 v[50:65], v[178:181], v[146:149], v[50:65]
	s_waitcnt vmcnt(17) lgkmcnt(5)
	v_mfma_f32_32x32x16_bf16 v[50:65], v[174:177], v[142:145], v[50:65]
	s_waitcnt vmcnt(16) lgkmcnt(4)
	v_mfma_f32_32x32x16_bf16 v[50:65], v[170:173], v[138:141], v[50:65]
	v_lshl_or_b32 v242, s3, 6, v219
	v_ashrrev_i32_e32 v243, 31, v242
	v_lshlrev_b64 v[244:245], 11, v[242:243]
	v_lshl_add_u64 v[244:245], v[202:203], 0, v[244:245]
	v_cvt_pk_bf16_f32 v82, v82, v83
	v_cvt_pk_bf16_f32 v83, v84, v85
	v_cvt_pk_bf16_f32 v84, v90, v91
	v_cvt_pk_bf16_f32 v85, v92, v93
	v_cvt_pk_bf16_f32 v86, v86, v87
	v_cvt_pk_bf16_f32 v87, v88, v89
	v_cvt_pk_bf16_f32 v88, v94, v95
	v_cvt_pk_bf16_f32 v89, v96, v97
	v_or_b32_e32 v90, 32, v242
	v_ashrrev_i32_e32 v91, 31, v90
	v_permlane32_swap_b32_e32 v82, v84
	v_permlane32_swap_b32_e32 v83, v85
	v_permlane32_swap_b32_e32 v86, v88
	v_permlane32_swap_b32_e32 v87, v89
	global_store_dwordx4 v[244:245], v[82:85], off
	global_store_dwordx4 v[244:245], v[86:89], off offset:16
	v_lshlrev_b64 v[90:91], 11, v[90:91]
	v_lshl_add_u64 v[90:91], v[202:203], 0, v[90:91]
	v_cvt_pk_bf16_f32 v66, v66, v67
	v_cvt_pk_bf16_f32 v67, v68, v69
	v_cvt_pk_bf16_f32 v68, v74, v75
	v_cvt_pk_bf16_f32 v69, v76, v77
	v_cvt_pk_bf16_f32 v70, v70, v71
	v_cvt_pk_bf16_f32 v71, v72, v73
	v_cvt_pk_bf16_f32 v72, v78, v79
	v_cvt_pk_bf16_f32 v73, v80, v81
	s_nop 1
	v_permlane32_swap_b32_e32 v66, v68
	v_permlane32_swap_b32_e32 v67, v69
	v_permlane32_swap_b32_e32 v70, v72
	v_permlane32_swap_b32_e32 v71, v73
	global_store_dwordx4 v[90:91], v[66:69], off
	global_store_dwordx4 v[90:91], v[70:73], off offset:16
	s_waitcnt vmcnt(19)
	ds_write_b128 v187, v[154:157]
	s_waitcnt vmcnt(18)
	ds_write_b128 v187, v[158:161] offset:8704
	s_waitcnt vmcnt(17)
	ds_write_b128 v220, v[162:165] offset:17408
	s_waitcnt vmcnt(16)
	ds_write_b128 v220, v[166:169] offset:26624
	s_and_saveexec_b64 s[14:15], vcc
	ds_write_b128 v228, v[98:101] offset:35840
	s_or_b64 exec, exec, s[14:15]
	ds_read_b128 v[170:173], v222 offset:63488
	ds_read_b128 v[174:177], v222 offset:63520
	ds_read_b128 v[178:181], v222 offset:63552
	ds_read_b128 v[182:185], v222 offset:63584
	s_waitcnt lgkmcnt(7)
	v_mfma_f32_32x32x16_bf16 v[34:49], v[190:193], v[150:153], v[34:49]
	s_waitcnt lgkmcnt(6)
	v_mfma_f32_32x32x16_bf16 v[34:49], v[194:197], v[146:149], v[34:49]
	s_waitcnt lgkmcnt(5)
	v_mfma_f32_32x32x16_bf16 v[34:49], v[234:237], v[142:145], v[34:49]
	s_waitcnt lgkmcnt(4)
	v_mfma_f32_32x32x16_bf16 v[34:49], v[238:241], v[138:141], v[34:49]
	ds_read_b128 v[190:193], v223 offset:13824
	ds_read_b128 v[194:197], v223 offset:13856
	ds_read_b128 v[234:237], v223 offset:13888
	ds_read_b128 v[238:241], v223 offset:13920
	s_waitcnt lgkmcnt(7)
	v_mfma_f32_32x32x16_bf16 v[18:33], v[170:173], v[150:153], v[18:33]
	s_waitcnt lgkmcnt(6)
	v_mfma_f32_32x32x16_bf16 v[18:33], v[174:177], v[146:149], v[18:33]
	s_waitcnt lgkmcnt(5)
	v_mfma_f32_32x32x16_bf16 v[18:33], v[178:181], v[142:145], v[18:33]
	s_waitcnt lgkmcnt(4)
	v_mfma_f32_32x32x16_bf16 v[18:33], v[182:185], v[138:141], v[18:33]
	s_waitcnt lgkmcnt(3)
	v_mfma_f32_32x32x16_bf16 v[2:17], v[190:193], v[150:153], v[2:17]
	s_waitcnt lgkmcnt(2)
	v_mfma_f32_32x32x16_bf16 v[2:17], v[194:197], v[146:149], v[2:17]
	s_waitcnt lgkmcnt(1)
	v_mfma_f32_32x32x16_bf16 v[2:17], v[234:237], v[142:145], v[2:17]
	s_waitcnt lgkmcnt(0)
	v_mfma_f32_32x32x16_bf16 v[2:17], v[238:241], v[138:141], v[2:17]
	s_lshl_b64 s[0:1], s[0:1], 15
	v_lshl_add_u64 v[138:139], v[206:207], 0, s[0:1]
	global_load_dwordx4 v[150:153], v[138:139], off
	global_load_dwordx4 v[146:149], v[138:139], off offset:32
	global_load_dwordx4 v[142:145], v[138:139], off offset:64
	s_nop 0
	global_load_dwordx4 v[138:141], v[138:139], off offset:96
	s_branch .LBB0_200
